# baseline (speedup 1.0000x reference)
; #define LAS __attribute__((address_space(3)))
; __device__ __forceinline__ void attn_load_kv(KVRegs& R, const bf16* Z, const bf16* KC, const bf16* VC, const float* sinks, int idx, int kvh, int tid) {
;     const bool sample = idx >= 256; const int c = idx & 31; const int row0 = idx * 64;
;     const int jmin = sample ? 0 : (c >= 2 ? 0 : 2 - c);
;     const int kr = tid >> 3, d0 = (tid & 7) * 8;
;     const v4u z = {0u, 0u, 0u, 0u};
;     R.k0 = z; R.k1 = z; R.k2 = z; R.v0 = z; R.v1 = z; R.v2 = z;
;     if (sample) {
;         const size_t off = ((size_t)((idx - 256) * 128 + kr)) * 256 + kvh * 64 + d0;
;         R.k0 = *(const v4u*)(KC + off); R.v0 = *(const v4u*)(VC + off); R.k1 = *(const v4u*)(KC + off + 64 * 256); R.v1 = *(const v4u*)(VC + off + 64 * 256);
;     } else {
;         const bf16* zr = Z + (size_t)(row0 - 128 + kr) * DIN + kvh * 64 + d0;
;         if (jmin <= 0) { R.k0 = *(const v4u*)(zr + 2048); R.v0 = *(const v4u*)(zr + 2304); }
;         if (jmin <= 1) { R.k1 = *(const v4u*)(zr + (size_t)64 * DIN + 2048); R.v1 = *(const v4u*)(zr + (size_t)64 * DIN + 2304); }
;     }
;     { const bf16* zr = Z + (size_t)(row0 + kr) * DIN + kvh * 64 + d0; R.k2 = *(const v4u*)(zr + 2048); R.v2 = *(const v4u*)(zr + 2304); }
;     { const int wid = tid >> 6, lane = tid & 63, g = wid >> 1, qh = wid & 1, r = lane & 31, h = lane >> 5;
;       const bf16* qp = Z + (size_t)(row0 + qh * 32 + r) * DIN + 1024 + (kvh * 4 + g) * 64 + 8 * h;
;       R.q0 = *(const bf16x8*)qp; R.q1 = *(const bf16x8*)(qp + 16); R.q2 = *(const bf16x8*)(qp + 32); R.q3 = *(const bf16x8*)(qp + 48); R.sink = sinks[kvh * 4 + g]; }
; __device__ __forceinline__ void attn_units(LAS unsigned char* lds, const bf16* Z, const bf16* KC, const bf16* VC, const float* sinks, bf16* MIXIN, int bx, int G, int tid, int wid, int lane) {
;     LAS bf16* Ks = (LAS bf16*)lds; LAS bf16* Vt = (LAS bf16*)(lds + 192 * ATT_KS * 2);
;     KVRegs R;
;     int u = bx;
;     if (u < NATT) attn_load_kv(R, Z, KC, VC, sinks, u >> 2, u & 3, tid);
.LBB0_52:
	s_and_b64 s[30:31], s[18:19], exec
	s_cselect_b32 s30, 64, 0
	v_ashrrev_i32_e32 v160, 7, v180
	s_waitcnt lgkmcnt(0)
	s_add_u32 s28, s28, s30
	v_lshl_add_u32 v2, s13, 2, v160
	v_and_b32_e32 v11, 31, v180
	v_lshrrev_b32_e32 v0, 1, v180
	s_addc_u32 s29, s29, 0
	v_ashrrev_i32_e32 v3, 31, v2
	v_and_or_b32 v161, v0, 32, v11
	v_lshl_add_u64 v[4:5], v[2:3], 2, s[28:29]
	v_or_b32_e32 v0, s12, v161
	v_mov_b64_e32 v[8:9], s[8:9]
	global_load_dword v156, v[4:5], off
	v_mad_i64_i32 v[4:5], s[12:13], v0, s75, v[8:9]
	v_lshlrev_b32_e32 v2, 6, v2
	v_lshrrev_b32_e32 v0, 2, v180
	v_ashrrev_i32_e32 v3, 31, v2
	v_and_b32_e32 v10, 8, v0
	v_mad_i64_i32 v[6:7], s[12:13], v6, s75, v[8:9]
	s_lshl_b32 s88, s5, 1
	v_lshl_add_u64 v[2:3], v[2:3], 1, v[4:5]
	v_lshlrev_b32_e32 v0, 1, v10
	v_lshl_add_u64 v[6:7], v[6:7], 0, s[88:89]
	v_mov_b32_e32 v151, v1
	v_lshl_add_u64 v[2:3], v[2:3], 0, v[0:1]
	v_lshl_add_u64 v[6:7], v[6:7], 0, v[150:151]
	global_load_dwordx4 v[138:141], v[2:3], off offset:2144
	global_load_dwordx4 v[142:145], v[2:3], off offset:2112
	global_load_dwordx4 v[146:149], v[2:3], off offset:2080
	s_nop 0
	global_load_dwordx4 v[2:5], v[2:3], off offset:2048
	v_add_co_u32_e32 v6, vcc, s80, v6
	v_lshrrev_b32_e32 v8, 5, v206
	s_nop 0
	v_addc_co_u32_e32 v7, vcc, 0, v7, vcc
	global_load_dwordx4 v[118:121], v[6:7], off offset:512
	global_load_dwordx4 v[114:117], v[6:7], off
	v_and_b32_e32 v12, 64, v204
	s_movk_i32 s12, 0x90
	v_mul_u32_u24_e32 v6, 0x188, v159
	v_lshlrev_b32_e32 v7, 1, v158
	v_xor_b32_e32 v9, 32, v204
	v_lshlrev_b32_e32 v16, 4, v8
	v_add_u32_e32 v12, 64, v12
	v_mul_lo_u32 v0, v158, s12
	v_or_b32_e32 v13, 32, v206
	v_or_b32_e32 v14, 0x60, v206
	v_or_b32_e32 v15, 0xa0, v206
	v_add3_u32 v164, 0, v6, v7
	v_mad_u32_u24 v7, v11, s12, 0
	v_lshlrev_b32_e32 v17, 3, v8
	v_add_u32_e32 v19, 0, v16
	v_cmp_lt_i32_e32 vcc, v9, v12
	s_ashr_i32 s42, s4, 7
	v_readlane_b32 s4, v240, 1
	v_add3_u32 v163, 0, v0, v150
	v_mul_u32_u24_e32 v6, 0x90, v11
	v_lshlrev_b32_e32 v0, 2, v8
	v_mul_u32_u24_e32 v8, 0x90, v13
	v_mul_u32_u24_e32 v14, 0x90, v14
	v_mul_u32_u24_e32 v15, 0x90, v15
	v_mul_u32_u24_e32 v18, 0x188, v11
	v_mul_u32_u24_e32 v13, 0x188, v13
	v_cndmask_b32_e32 v9, v204, v9, vcc
	v_add_u32_e32 v167, v7, v16
	s_lshl_b32 s4, s4, 5
	v_sub_u32_e32 v7, v19, v17
	v_add_u32_e32 v162, 0xffff8000, v158
	s_mov_b32 s5, s2
	v_add_u32_e32 v165, 0x2400, v163
	v_add_u32_e32 v166, 0x4800, v163
	v_lshlrev_b32_e32 v152, 1, v10
	v_lshlrev_b32_e32 v168, 2, v9
	s_lshl_b32 s43, s2, 2
	s_lshl_b32 s44, s3, 2
	v_add_u32_e32 v169, v19, v8
	v_add_u32_e32 v170, v19, v6
	v_add_u32_e32 v171, v19, v14
	v_add_u32_e32 v172, v19, v15
	v_and_or_b32 v154, s4, 32, v11
	v_add_u32_e32 v173, v7, v18
	v_add_u32_e32 v174, v7, v13
	v_lshlrev_b32_e32 v0, 1, v0
	s_waitcnt vmcnt(6)
	v_mov_b32_e32 v151, v156
	s_waitcnt vmcnt(5)
	v_mov_b64_e32 v[134:135], v[138:139]
	s_waitcnt vmcnt(4)
	v_mov_b64_e32 v[130:131], v[142:143]
	s_waitcnt vmcnt(3)
	v_mov_b64_e32 v[126:127], v[146:147]
	s_waitcnt vmcnt(2)
	v_mov_b64_e32 v[124:125], v[4:5]
	v_mov_b64_e32 v[122:123], v[2:3]
	v_mov_b64_e32 v[128:129], v[148:149]
	v_mov_b64_e32 v[132:133], v[144:145]
	v_mov_b64_e32 v[136:137], v[140:141]
	s_waitcnt vmcnt(0)
	s_branch .LBB0_54

; __device__ __forceinline__ void attn_load_kv(KVRegs& R, const bf16* Z, const bf16* KC, const bf16* VC, const float* sinks, int idx, int kvh, int tid) {
;     const bool sample = idx >= 256; const int c = idx & 31; const int row0 = idx * 64;
;     const int jmin = sample ? 0 : (c >= 2 ? 0 : 2 - c);
;     const int kr = tid >> 3, d0 = (tid & 7) * 8;
;     const v4u z = {0u, 0u, 0u, 0u};
;     R.k0 = z; R.k1 = z; R.k2 = z; R.v0 = z; R.v1 = z; R.v2 = z;
;     if (sample) {
;         const size_t off = ((size_t)((idx - 256) * 128 + kr)) * 256 + kvh * 64 + d0;
;         R.k0 = *(const v4u*)(KC + off); R.v0 = *(const v4u*)(VC + off); R.k1 = *(const v4u*)(KC + off + 64 * 256); R.v1 = *(const v4u*)(VC + off + 64 * 256);
;     } else {
;         const bf16* zr = Z + (size_t)(row0 - 128 + kr) * DIN + kvh * 64 + d0;
;         if (jmin <= 0) { R.k0 = *(const v4u*)(zr + 2048); R.v0 = *(const v4u*)(zr + 2304); }
;         if (jmin <= 1) { R.k1 = *(const v4u*)(zr + (size_t)64 * DIN + 2048); R.v1 = *(const v4u*)(zr + (size_t)64 * DIN + 2304); }
;     }
;     { const bf16* zr = Z + (size_t)(row0 + kr) * DIN + kvh * 64 + d0; R.k2 = *(const v4u*)(zr + 2048); R.v2 = *(const v4u*)(zr + 2304); }
; __device__ __forceinline__ void attn_units(LAS unsigned char* lds, const bf16* Z, const bf16* KC, const bf16* VC, const float* sinks, bf16* MIXIN, int bx, int G, int tid, int wid, int lane) {
;     ...
;     for (; u < NATT; u += G) {
;         const int idx = u >> 2, kvh = u & 3;
;         const bool sample = idx >= 256; const int c = idx & 31; const int row0 = idx * 64;
;         const int jmin = sample ? 0 : (c >= 2 ? 0 : 2 - c);
;         { const int kr = tid >> 3, d0 = (tid & 7) * 8;
;           attn_stage(Ks, Vt, R.k0, R.v0, kr, d0); attn_stage(Ks, Vt, R.k1, R.v1, 64 + kr, d0); attn_stage(Ks, Vt, R.k2, R.v2, 128 + kr, d0); }
;         const int g = wid >> 1, qh = wid & 1, r = lane & 31, h = lane >> 5;
;         const int head = kvh * 4 + g; const size_t qrow = (size_t)row0 + qh * 32 + r;
;         const bf16x8 bq[4] = {R.q0, R.q1, R.q2, R.q3};
;         const float sink = R.sink;
;         __syncthreads();
;         if (u + G < NATT) attn_load_kv(R, Z, KC, VC, sinks, (u + G) >> 2, (u + G) & 3, tid);
.LBB0_54:
	s_add_i32 s45, s5, s3
	s_cmpk_gt_i32 s45, 0x47f
	s_cselect_b64 s[30:31], -1, 0
	s_and_b64 vcc, exec, s[30:31]
	ds_write_b128 v163, v[98:101]
	ds_write_b16 v164, v102 offset:27648
	ds_write_b16_d16_hi v164, v102 offset:28040
	ds_write_b16 v164, v103 offset:28432
	ds_write_b16_d16_hi v164, v103 offset:28824
	ds_write_b16 v164, v104 offset:29216
	ds_write_b16_d16_hi v164, v104 offset:29608
	ds_write_b16 v164, v105 offset:30000
	ds_write_b16_d16_hi v164, v105 offset:30392
	ds_write_b128 v165, v[106:109]
	ds_write_b16 v164, v110 offset:27776
	ds_write_b16_d16_hi v164, v110 offset:28168
	ds_write_b16 v164, v111 offset:28560
	ds_write_b16_d16_hi v164, v111 offset:28952
	ds_write_b16 v164, v112 offset:29344
	ds_write_b16_d16_hi v164, v112 offset:29736
	ds_write_b16 v164, v113 offset:30128
	ds_write_b16_d16_hi v164, v113 offset:30520
	s_waitcnt vmcnt(8)
	ds_write_b128 v166, v[114:117]
	ds_write_b16 v164, v118 offset:27904
	ds_write_b16_d16_hi v164, v118 offset:28296
	ds_write_b16 v164, v119 offset:28688
	ds_write_b16_d16_hi v164, v119 offset:29080
	ds_write_b16 v164, v120 offset:29472
	ds_write_b16_d16_hi v164, v120 offset:29864
	ds_write_b16 v164, v121 offset:30256
	ds_write_b16_d16_hi v164, v121 offset:30648
	s_waitcnt lgkmcnt(0)
	s_barrier
	s_cbranch_vccnz .LBB0_62
	s_ashr_i32 s33, s45, 2
	s_and_b32 s4, s45, 3
	s_lshl_b32 s12, s33, 6
	s_lshl_b32 s13, s4, 6
	s_cmpk_lt_i32 s33, 0x100
	s_mov_b64 s[34:35], -1
	v_add_u32_e32 v8, s12, v158
	s_cbranch_scc0 .LBB0_59
	s_and_b32 s34, s33, 31
	s_sub_i32 s35, 2, s34
	v_add_u32_e32 v9, s12, v158
	s_cmp_lt_u32 s34, 2
	v_add_u32_e32 v10, 0xffffff80, v9
	v_mov_b64_e32 v[6:7], s[8:9]
	s_cselect_b32 s34, s35, 0
	v_mad_i64_i32 v[6:7], s[36:37], v10, s75, v[6:7]
	s_lshl_b32 s88, s13, 1
	v_lshl_add_u64 v[6:7], v[6:7], 0, s[88:89]
	v_mov_b32_e32 v151, v1
	s_cmp_lg_u32 s34, 0
	v_lshl_add_u64 v[6:7], v[6:7], 0, v[150:151]
	s_cbranch_scc0 .LBB0_72
	v_mov_b32_e32 v98, v1
	v_mov_b32_e32 v99, v1
	v_mov_b32_e32 v100, v1
	v_mov_b32_e32 v101, v1
	v_mov_b32_e32 v102, v1
	v_mov_b32_e32 v103, v1
	v_mov_b32_e32 v104, v1
	v_mov_b32_e32 v105, v1
	s_cmp_gt_u32 s34, 1
	s_cbranch_scc1 .LBB0_73

; #define LAS __attribute__((address_space(3)))
; __device__ __forceinline__ void pool_units(LAS unsigned char* lds, const bf16* Z, const float* state, const bf16* Wpt, const float* pscale, bf16* MIXIN, int bx, int G, int tid, int wid, int lane) {
;     LAS bf16* Ul = (LAS bf16*)lds; LAS bf16* Dl = (LAS bf16*)(lds + PL_D_OFF);
;     PRegs R;
;     int u = bx + (G >> 1); if (u >= G) u -= G;
;     if (u < NATT) pool_load(R, Z, state, u >> 2, u & 3, tid);
; #pragma unroll 1
;     for (; u < NATT; u += G) {
;         const int idx = u >> 2, g = u & 3;
;         const bool sample = idx >= 256; const int c = idx & 31; const int row0 = idx * 64; const int w = 2 << g;
;         { const int rb = tid >> 5, cgx = tid & 31;
;           *(LAS v4u*)(Ul + rb * PL_DS + cgx * 8) = R.c0; *(LAS v4u*)(Ul + (rb + 16) * PL_DS + cgx * 8) = R.c1; *(LAS v4u*)(Ul + (rb + 32) * PL_DS + cgx * 8) = R.c2;
;           *(LAS v4u*)(Ul + (rb + 48) * PL_DS + cgx * 8) = R.c3; if (rb + 64 < 79) *(LAS v4u*)(Ul + (rb + 64) * PL_DS + cgx * 8) = R.c4; }
;         const int fr = lane & 15, fq = lane >> 4;
;         const bf16* wb = Wpt + (size_t)g * 65536 + (size_t)(32 * wid + fr) * 256 + fq * 8;
.LBB0_120:
	s_andn2_b64 vcc, exec, s[28:29]
	s_cbranch_vccnz .LBB0_170
	s_and_b64 s[12:13], s[18:19], exec
	s_cselect_b32 s12, 0x1000, 0
	v_lshl_add_u32 v106, v107, 1, 0
	s_add_u32 s28, s26, s12
	v_mad_u64_u32 v[108:109], s[12:13], v104, s91, v[106:107]
	v_readlane_b32 s12, v240, 1
	s_addc_u32 s29, s27, 0
	v_and_b32_e32 v109, 15, v180
	s_lshl_b32 s12, s12, 5
	s_waitcnt vmcnt(0)
	v_or_b32_e32 v2, s12, v109
	v_ashrrev_i32_e32 v3, 31, v2
	v_lshlrev_b64 v[2:3], 9, v[2:3]
	v_lshl_add_u64 v[2:3], s[14:15], 0, v[2:3]
	v_and_b32_e32 v0, 48, v206
	v_lshl_add_u64 v[2:3], v[2:3], 0, v[0:1]
	s_mov_b64 s[26:27], 0x5400000
	s_ashr_i32 s13, s12, 31
	v_lshl_add_u64 v[110:111], v[2:3], 0, s[26:27]
	s_lshl_b64 s[26:27], s[12:13], 2
	s_movk_i32 s13, 0xffee
	v_lshrrev_b32_e32 v2, 2, v206
	v_cmp_lt_i32_e64 s[30:31], s13, v104
	s_movk_i32 s13, 0xffef
	s_add_u32 s26, s28, s26
	v_cmp_gt_i32_e64 s[44:45], s13, v104
	s_movk_i32 s13, 0xffde
	v_and_or_b32 v159, v2, 12, s12
	s_movk_i32 s12, 0x840
	s_addc_u32 s27, s29, s27
	v_cmp_lt_i32_e64 s[34:35], s13, v104
	s_movk_i32 s13, 0xffdf
	v_lshlrev_b32_e32 v158, 2, v104
	v_mul_lo_u32 v2, v104, s12
	s_add_i32 s12, s2, s3
	v_cmp_gt_i32_e64 s[46:47], s13, v104
	s_movk_i32 s13, 0xffce
	v_or_b32_e32 v160, 1, v158
	v_or_b32_e32 v17, 48, v206
	s_add_i32 s12, s12, s5
	v_lshl_add_u64 v[112:113], s[26:27], 0, v[0:1]
	v_add_u32_e32 v114, 16, v104
	v_add_u32_e32 v116, 32, v104
	v_add_u32_e32 v118, 48, v104
	v_cmp_lt_i32_e64 s[36:37], s13, v104
	s_movk_i32 s13, 0xffcf
	v_add_u32_e32 v120, 64, v104
	v_add_u32_e32 v0, 0, v0
	v_mul_lo_u32 v3, v160, s91
	v_mul_u32_u24_e32 v16, 0x210, v109
	v_mul_u32_u24_e32 v17, 0x210, v17
	s_sub_i32 s5, s12, s11
	v_cmp_gt_i32_e64 s[40:41], 15, v104
	v_cmp_lt_i32_e64 s[26:27], 14, v104
	v_ashrrev_i32_e32 v105, 31, v104
	v_add_u32_e32 v152, -15, v104
	v_cmp_lt_i32_e64 s[28:29], -2, v104
	v_cmp_gt_i32_e64 s[42:43], -1, v104
	v_ashrrev_i32_e32 v115, 31, v114
	v_add_u32_e32 v153, 1, v104
	v_ashrrev_i32_e32 v117, 31, v116
	v_add_u32_e32 v154, 17, v104
	v_ashrrev_i32_e32 v119, 31, v118
	v_add_u32_e32 v156, 33, v104
	v_cmp_gt_i32_e64 s[48:49], s13, v104
	v_ashrrev_i32_e32 v121, 31, v120
	v_add_u32_e32 v157, 49, v104
	v_or_b32_e32 v161, 2, v158
	v_or_b32_e32 v162, 3, v158
	s_lshl_b32 s11, s5, 8
	s_lshl_b32 s60, s3, 8
	v_add_u32_e32 v163, v106, v2
	v_add_u32_e32 v164, v106, v3
	v_add_u32_e32 v165, v0, v16
	v_add_u32_e32 v166, v0, v17
	s_waitcnt vmcnt(0)
	s_branch .LBB0_125

; #define LAS __attribute__((address_space(3)))
; __device__ __forceinline__ unsigned pk2(float lo, float hi) { return f2bf(lo) | (f2bf(hi) << 16); }
; __device__ __forceinline__ v4u pool_load_piece(const bf16* Z, const float* state, int idx, int g, int rr, int cgx) {
;     const bool sample = idx >= 256; const int c = idx & 31; const int row0 = idx * 64; const int ch = g * 256 + cgx * 8;
;     v4u o = {0u, 0u, 0u, 0u};
;     if (rr >= 0 || (!sample && c > 0)) o = *(const v4u*)(Z + (size_t)(row0 + rr) * DIN + ch);
;     else if (sample) { const float* sp = state + ((size_t)(idx - 256) * 15 + (15 + rr)) * DPOOL + ch; const f32x4 a0 = *(const f32x4*)sp, a1 = *(const f32x4*)(sp + 4);
;         o.x = pk2(a0.x, a0.y); o.y = pk2(a0.z, a0.w); o.z = pk2(a1.x, a1.y); o.w = pk2(a1.z, a1.w); }
; __device__ __forceinline__ void pool_units(LAS unsigned char* lds, const bf16* Z, const float* state, const bf16* Wpt, const float* pscale, bf16* MIXIN, int bx, int G, int tid, int wid, int lane) {
;     ...
;     for (; u < NATT; u += G) {
;         const int idx = u >> 2, g = u & 3;
;         const bool sample = idx >= 256; const int c = idx & 31; const int row0 = idx * 64; const int w = 2 << g;
;         { const int rb = tid >> 5, cgx = tid & 31;
;           *(LAS v4u*)(Ul + rb * PL_DS + cgx * 8) = R.c0; *(LAS v4u*)(Ul + (rb + 16) * PL_DS + cgx * 8) = R.c1; *(LAS v4u*)(Ul + (rb + 32) * PL_DS + cgx * 8) = R.c2;
;           *(LAS v4u*)(Ul + (rb + 48) * PL_DS + cgx * 8) = R.c3; if (rb + 64 < 79) *(LAS v4u*)(Ul + (rb + 64) * PL_DS + cgx * 8) = R.c4; }
;         const int fr = lane & 15, fq = lane >> 4;
;         const bf16* wb = Wpt + (size_t)g * 65536 + (size_t)(32 * wid + fr) * 256 + fq * 8;
;         bf16x8 wa[8][2];
; #pragma unroll
;         for (int ks = 0; ks < 8; ++ks)
; #pragma unroll
;             for (int nt = 0; nt < 2; ++nt) wa[ks][nt] = *(const bf16x8*)(wb + nt * 16 * 256 + ks * 32);
;         f32x4 psc[2];
; #pragma unroll
;         for (int nt = 0; nt < 2; ++nt) psc[nt] = *(const f32x4*)(pscale + g * 256 + 32 * wid + 16 * nt + fq * 4);
;         __syncthreads();
;         if (u + G < NATT) pool_load(R, Z, state, (u + G) >> 2, (u + G) & 3, tid);
.LBB0_125:
	s_waitcnt vmcnt(8)
	ds_write_b128 v108, v[4:7]
	ds_write_b128 v108, v[8:11] offset:8448
	ds_write_b128 v108, v[12:15] offset:16896
	ds_write_b128 v108, v[20:23] offset:25344
	s_and_saveexec_b64 s[38:39], s[40:41]
	ds_write_b128 v108, v[52:55] offset:33792
	s_or_b64 exec, exec, s[38:39]
	s_and_b32 s5, s4, 3
	s_lshl_b32 s88, s5, 17
	v_lshl_add_u64 v[2:3], v[110:111], 0, s[88:89]
	v_add_co_u32_e32 v16, vcc, 0x2000, v2
	s_lshl_b32 s88, s5, 10
	s_nop 0
	v_addc_co_u32_e32 v17, vcc, 0, v3, vcc
	global_load_dwordx4 v[88:91], v[2:3], off
	global_load_dwordx4 v[84:87], v[2:3], off offset:64
	global_load_dwordx4 v[92:95], v[16:17], off
	global_load_dwordx4 v[80:83], v[16:17], off offset:64
	global_load_dwordx4 v[76:79], v[2:3], off offset:128
	global_load_dwordx4 v[68:71], v[2:3], off offset:192
	global_load_dwordx4 v[72:75], v[16:17], off offset:128
	global_load_dwordx4 v[64:67], v[16:17], off offset:192
	global_load_dwordx4 v[60:63], v[2:3], off offset:256
	global_load_dwordx4 v[48:51], v[2:3], off offset:320
	global_load_dwordx4 v[56:59], v[16:17], off offset:256
	global_load_dwordx4 v[44:47], v[16:17], off offset:320
	global_load_dwordx4 v[40:43], v[2:3], off offset:384
	global_load_dwordx4 v[32:35], v[2:3], off offset:448
	global_load_dwordx4 v[36:39], v[16:17], off offset:384
	global_load_dwordx4 v[28:31], v[16:17], off offset:448
	v_lshl_add_u64 v[2:3], v[112:113], 0, s[88:89]
	global_load_dwordx4 v[24:27], v[2:3], off
	global_load_dwordx4 v[16:19], v[2:3], off offset:64
	s_add_i32 s61, s4, s3
	s_cmpk_gt_i32 s61, 0x47f
	s_cselect_b64 s[96:97], -1, 0
	s_and_b64 vcc, exec, s[96:97]
	s_waitcnt lgkmcnt(0)
	s_barrier
	s_cbranch_vccnz .LBB0_124
	s_ashr_i32 s12, s61, 2
	s_cmpk_lt_i32 s12, 0x100
	s_cselect_b64 s[82:83], -1, 0
	s_cmpk_gt_i32 s12, 0xff
	s_cselect_b64 s[50:51], -1, 0
	s_and_b32 s13, s11, 0x300
	v_or_b32_e32 v96, s13, v107
	s_mov_b64 s[52:53], s[26:27]
	s_and_saveexec_b64 s[38:39], s[40:41]
	s_cbranch_execz .LBB0_132
	s_and_b32 s13, s61, 0x7c
	s_cmp_eq_u32 s13, 0
	s_cselect_b64 s[62:63], -1, 0
	s_xor_b64 s[64:65], s[82:83], -1
	s_or_b64 s[62:63], s[64:65], s[62:63]
	s_mov_b64 s[52:53], -1
	s_and_b64 vcc, exec, s[62:63]
	s_cbranch_vccz .LBB0_162
	s_andn2_b64 vcc, exec, s[50:51]
	s_cbranch_vccnz .LBB0_161
	s_add_i32 s13, s12, 0xffffff00
	v_mad_u64_u32 v[2:3], s[52:53], s13, 15, v[104:105]
	v_lshlrev_b64 v[2:3], 12, v[2:3]
	v_lshl_add_u64 v[2:3], s[24:25], 0, v[2:3]
	v_lshlrev_b32_e32 v0, 2, v96
	v_lshl_add_u64 v[6:7], v[2:3], 0, v[0:1]
	global_load_dwordx4 v[2:5], v[6:7], off
	s_nop 0
	global_load_dwordx4 v[6:9], v[6:7], off offset:16
	s_mov_b64 s[52:53], 0
	s_waitcnt vmcnt(1)
	v_bfe_u32 v0, v2, 16, 1
	v_bfe_u32 v10, v3, 16, 1
	v_bfe_u32 v11, v4, 16, 1
	s_waitcnt vmcnt(0)
	v_bfe_u32 v13, v6, 16, 1
	v_bfe_u32 v14, v7, 16, 1
	v_bfe_u32 v15, v8, 16, 1
	v_bfe_u32 v12, v5, 16, 1
	v_bfe_u32 v20, v9, 16, 1
	v_add3_u32 v0, v2, v0, s84
	v_add3_u32 v2, v3, v10, s84
	v_add3_u32 v3, v4, v11, s84
	v_add3_u32 v4, v6, v13, s84
	v_add3_u32 v6, v7, v14, s84
	v_add3_u32 v7, v8, v15, s84
	v_add3_u32 v5, v5, v12, s84
	v_add3_u32 v8, v9, v20, s84
	v_lshrrev_b32_e32 v0, 16, v0
	v_lshrrev_b32_e32 v3, 16, v3
	v_lshrrev_b32_e32 v9, 16, v4
	v_lshrrev_b32_e32 v7, 16, v7
	v_and_or_b32 v4, v2, s85, v0
	v_and_or_b32 v5, v5, s85, v3
	v_and_or_b32 v6, v6, s85, v9
	v_and_or_b32 v7, v8, s85, v7
	s_branch .LBB0_162
